# also use DPP/permlane-swap butterfly in the initial x->rmsnorm rows pass
# baseline (speedup 1.0000x reference)
.LBB0_45:
	s_lshl_b64 s[8:9], s[28:29], 12
	s_waitcnt vmcnt(3)
	v_pk_mul_f32 v[24:25], v[38:39], v[38:39]
	v_pk_mul_f32 v[26:27], v[36:37], v[36:37]
	s_add_u32 s8, s18, s8
	v_pk_mov_b32 v[28:29], v[26:27], v[24:25] op_sel:[1,0]
	v_mov_b32_e32 v27, v25
	s_addc_u32 s9, s19, s9
	v_pk_add_f32 v[60:61], v[28:29], v[26:27]
	v_lshl_add_u64 v[26:27], v[48:49], 4, s[8:9]
	global_load_dwordx4 v[44:47], v[26:27], off
	global_load_dwordx4 v[28:31], v[26:27], off offset:1024
	s_waitcnt vmcnt(4)
	v_pk_mul_f32 v[24:25], v[34:35], v[34:35]
	v_pk_mul_f32 v[62:63], v[32:33], v[32:33]
	global_load_dwordx4 v[40:43], v[26:27], off offset:2048
	v_pk_mov_b32 v[64:65], v[62:63], v[24:25] op_sel:[1,0]
	v_mov_b32_e32 v63, v25
	global_load_dwordx4 v[24:27], v[26:27], off offset:3072
	v_pk_add_f32 v[62:63], v[64:65], v[62:63]
	s_waitcnt vmcnt(4)
	v_mul_f32_e32 v59, v16, v16
	v_mul_f32_e32 v64, v17, v17
	v_pk_add_f32 v[60:61], v[60:61], v[60:61] op_sel:[0,1] op_sel_hi:[1,0]
	v_pk_add_f32 v[62:63], v[62:63], v[62:63] op_sel:[0,1] op_sel_hi:[1,0]
	v_mov_b32_e32 v61, v59
	v_mov_b32_e32 v63, v64
	v_pk_add_f32 v[60:61], v[60:61], v[62:63]
	v_mul_f32_e32 v62, v21, v21
	v_mul_f32_e32 v65, v18, v18
	v_pk_fma_f32 v[62:63], v[20:21], v[20:21], v[62:63] op_sel_hi:[1,1,0]
	v_mul_f32_e32 v64, v23, v23
	v_mul_f32_e32 v66, v19, v19
	v_mov_b32_e32 v63, v65
	v_pk_fma_f32 v[64:65], v[22:23], v[22:23], v[64:65] op_sel_hi:[1,1,0]
	s_ashr_i32 s5, s4, 31
	v_mov_b32_e32 v65, v66
	v_pk_add_f32 v[62:63], v[62:63], v[64:65]
	s_lshl_b64 s[4:5], s[4:5], 11
	v_pk_add_f32 v[60:61], v[60:61], v[62:63]
	s_waitcnt vmcnt(1)
	v_mul_f32_e32 v62, v41, v41
	v_add_f32_e32 v59, v60, v61
	s_nop 1
	v_mov_b32_dpp v60, v59 quad_perm:[1,0,3,2] row_mask:0xf bank_mask:0xf
	v_mul_f32_e32 v63, v43, v43
	s_waitcnt vmcnt(0)
	v_mul_f32_e32 v64, v25, v25
	v_mul_f32_e32 v65, v27, v27
	v_fmac_f32_e32 v62, v40, v40
	s_waitcnt lgkmcnt(0)
	v_add_f32_e32 v59, v59, v60
	s_nop 1
	v_mov_b32_dpp v60, v59 quad_perm:[2,3,0,1] row_mask:0xf bank_mask:0xf
	v_fmac_f32_e32 v63, v42, v42
	v_fmac_f32_e32 v64, v24, v24
	v_fmac_f32_e32 v65, v26, v26
	s_waitcnt lgkmcnt(0)
	v_add_f32_e32 v59, v59, v60
	s_nop 1
	v_mov_b32_dpp v60, v59 row_half_mirror row_mask:0xf bank_mask:0xf
	s_waitcnt lgkmcnt(0)
	v_add_f32_e32 v59, v59, v60
	s_nop 1
	v_mov_b32_dpp v60, v59 row_mirror row_mask:0xf bank_mask:0xf
	s_waitcnt lgkmcnt(0)
	v_add_f32_e32 v59, v59, v60
	v_mov_b32_e32 v60, v59
	s_nop 1
	v_permlane16_swap_b32 v59, v60
	s_waitcnt lgkmcnt(0)
	v_add_f32_e32 v59, v59, v60
	v_mov_b32_e32 v60, v59
	s_nop 1
	v_permlane32_swap_b32 v59, v60
	s_waitcnt lgkmcnt(0)
	v_add_f32_e32 v59, v59, v60
	v_fmamk_f32 v59, v59, 0x3a800000, v58
	v_mul_f32_e32 v60, 0x4b800000, v59
	v_cmp_gt_f32_e32 vcc, s16, v59
	s_nop 1
	v_cndmask_b32_e32 v59, v59, v60, vcc
	v_rsq_f32_e32 v59, v59
	s_nop 0
	v_mul_f32_e32 v60, 0x45800000, v59
	v_cndmask_b32_e32 v60, v59, v60, vcc
	v_pk_mul_f32 v[36:37], v[36:37], v[60:61] op_sel_hi:[1,0]
	v_pk_mul_f32 v[38:39], v[38:39], v[60:61] op_sel_hi:[1,0]
	v_pk_mul_f32 v[36:37], v[0:1], v[36:37]
	v_pk_mul_f32 v[38:39], v[2:3], v[38:39]
	v_pk_mul_f32 v[32:33], v[32:33], v[60:61] op_sel_hi:[1,0]
	v_pk_mul_f32 v[34:35], v[34:35], v[60:61] op_sel_hi:[1,0]
	v_cvt_pk_bf16_f32 v36, v36, v37
	v_cvt_pk_bf16_f32 v37, v38, v39
	v_mul_f32_e32 v38, v45, v45
	v_mul_f32_e32 v39, v47, v47
	v_mul_f32_e32 v59, v29, v29
	v_mul_f32_e32 v61, v31, v31
	v_fmac_f32_e32 v38, v44, v44
	v_fmac_f32_e32 v39, v46, v46
	v_fmac_f32_e32 v59, v28, v28
	v_fmac_f32_e32 v61, v30, v30
	v_add_f32_e32 v38, v38, v39
	v_add_f32_e32 v39, v59, v61
	v_add_f32_e32 v59, v62, v63
	v_add_f32_e32 v38, v38, v39
	v_add_f32_e32 v38, v38, v59
	v_add_f32_e32 v39, v64, v65
	v_add_f32_e32 v59, v38, v39
	s_nop 1
	v_mov_b32_dpp v61, v59 quad_perm:[1,0,3,2] row_mask:0xf bank_mask:0xf
	v_lshl_add_u64 v[38:39], v[50:51], 0, s[4:5]
	global_store_dwordx2 v[38:39], v[36:37], off
	v_pk_mul_f32 v[32:33], v[4:5], v[32:33]
	v_pk_mul_f32 v[34:35], v[6:7], v[34:35]
	s_waitcnt lgkmcnt(0)
	v_add_f32_e32 v36, v59, v61
	s_nop 1
	v_mov_b32_dpp v37, v36 quad_perm:[2,3,0,1] row_mask:0xf bank_mask:0xf
	v_cvt_pk_bf16_f32 v32, v32, v33
	v_cvt_pk_bf16_f32 v33, v34, v35
	global_store_dwordx2 v[38:39], v[32:33], off offset:512
	v_pk_mul_f32 v[20:21], v[20:21], v[60:61] op_sel_hi:[1,0]
	s_waitcnt lgkmcnt(0)
	v_add_f32_e32 v32, v36, v37
	s_nop 1
	v_mov_b32_dpp v33, v32 row_half_mirror row_mask:0xf bank_mask:0xf
	v_pk_mul_f32 v[22:23], v[22:23], v[60:61] op_sel_hi:[1,0]
	v_pk_mul_f32 v[20:21], v[8:9], v[20:21]
	v_pk_mul_f32 v[22:23], v[10:11], v[22:23]
	v_cvt_pk_bf16_f32 v20, v20, v21
	s_waitcnt lgkmcnt(0)
	v_add_f32_e32 v32, v32, v33
	s_nop 1
	v_mov_b32_dpp v33, v32 row_mirror row_mask:0xf bank_mask:0xf
	v_cvt_pk_bf16_f32 v21, v22, v23
	v_pk_mul_f32 v[16:17], v[16:17], v[60:61] op_sel_hi:[1,0]
	global_store_dwordx2 v[38:39], v[20:21], off offset:1024
	v_pk_mul_f32 v[16:17], v[12:13], v[16:17]
	s_waitcnt lgkmcnt(0)
	v_add_f32_e32 v22, v32, v33
	ds_bpermute_b32 v23, v56, v22
	v_cvt_pk_bf16_f32 v20, v16, v17
	v_pk_mul_f32 v[18:19], v[18:19], v[60:61] op_sel_hi:[1,0]
	s_andn2_b64 vcc, exec, s[14:15]
	v_pk_mul_f32 v[18:19], v[14:15], v[18:19]
	s_waitcnt lgkmcnt(0)
	v_add_f32_e32 v16, v22, v23
	ds_bpermute_b32 v17, v57, v16
	v_cvt_pk_bf16_f32 v21, v18, v19
	global_store_dwordx2 v[38:39], v[20:21], off offset:1536
	s_cbranch_vccnz .LBB0_30
	s_waitcnt lgkmcnt(0)
	v_add_f32_e32 v16, v16, v17
	v_fmamk_f32 v16, v16, 0x3a800000, v58
	v_mul_f32_e32 v17, 0x4b800000, v16
	v_cmp_gt_f32_e32 vcc, s16, v16
	s_ashr_i32 s13, s12, 31
	s_lshl_b64 s[4:5], s[12:13], 11
	v_cndmask_b32_e32 v16, v16, v17, vcc
	v_rsq_f32_e32 v16, v16
	v_lshl_add_u64 v[18:19], v[50:51], 0, s[4:5]
	v_mul_f32_e32 v17, 0x45800000, v16
	v_cndmask_b32_e32 v16, v16, v17, vcc
	v_pk_mul_f32 v[20:21], v[44:45], v[16:17] op_sel_hi:[1,0]
	v_pk_mul_f32 v[22:23], v[46:47], v[16:17] op_sel_hi:[1,0]
	v_pk_mul_f32 v[20:21], v[0:1], v[20:21]
	v_pk_mul_f32 v[22:23], v[2:3], v[22:23]
	v_cvt_pk_bf16_f32 v20, v20, v21
	s_nop 0
	v_cvt_pk_bf16_f32 v21, v22, v23
	global_store_dwordx2 v[18:19], v[20:21], off
	v_pk_mul_f32 v[20:21], v[28:29], v[16:17] op_sel_hi:[1,0]
	v_pk_mul_f32 v[22:23], v[30:31], v[16:17] op_sel_hi:[1,0]
	v_pk_mul_f32 v[20:21], v[4:5], v[20:21]
	v_pk_mul_f32 v[22:23], v[6:7], v[22:23]
	v_cvt_pk_bf16_f32 v20, v20, v21
	s_nop 0
	v_cvt_pk_bf16_f32 v21, v22, v23
	global_store_dwordx2 v[18:19], v[20:21], off offset:512
	v_pk_mul_f32 v[20:21], v[40:41], v[16:17] op_sel_hi:[1,0]
	v_pk_mul_f32 v[22:23], v[42:43], v[16:17] op_sel_hi:[1,0]
	v_pk_mul_f32 v[20:21], v[8:9], v[20:21]
	v_pk_mul_f32 v[22:23], v[10:11], v[22:23]
	v_cvt_pk_bf16_f32 v20, v20, v21
	s_nop 0
	v_cvt_pk_bf16_f32 v21, v22, v23
	global_store_dwordx2 v[18:19], v[20:21], off offset:1024
	v_pk_mul_f32 v[20:21], v[24:25], v[16:17] op_sel_hi:[1,0]
	v_pk_mul_f32 v[16:17], v[26:27], v[16:17] op_sel_hi:[1,0]
	v_pk_mul_f32 v[20:21], v[12:13], v[20:21]
	v_pk_mul_f32 v[16:17], v[14:15], v[16:17]
	v_cvt_pk_bf16_f32 v20, v20, v21
	s_nop 0
	v_cvt_pk_bf16_f32 v21, v16, v17
	global_store_dwordx2 v[18:19], v[20:21], off offset:1536
	s_branch .LBB0_30
